# GU K-loop: first trip of each later unit waits vmcnt(16) in its first two load segments (the previous epilogue's 8 H stores sit in the in-order queue), other trips unchanged
# speedup vs baseline: 1.0030x; 1.0030x over previous
; #define PG8_STAGE(bufoff, gbase, voff) do { _Pragma("unroll") for (int _i = 0; _i < 2; ++_i) \
;         __builtin_amdgcn_global_load_lds((const unsigned*)((const char*)(gbase) + (voff)[_i]), (PG8_LAS unsigned*)(lds + (bufoff) + ldsw + _i * 8192), 16, 0, 0); } while (0)
; #define PG8_LDA(dst, b, h) do { _Pragma("unroll") for (int m = 0; m < 4; ++m) _Pragma("unroll") for (int k = 0; k < 2; ++k) dst[m][k] = *(const PG8_LAS bf16x8*)(lds + PG8_SA(b, h) + aoff + m * 2048 + k * 1024); } while (0)
; #define PG8_LDB(dst, b, h) do { _Pragma("unroll") for (int n = 0; n < 2; ++n) _Pragma("unroll") for (int k = 0; k < 2; ++k) dst[n][k] = *(const PG8_LAS bf16x8*)(lds + PG8_SB(b, h) + boff + n * 2048 + k * 1024); } while (0)
; #define PG8_MMA(ai, bj, At, Bt) do { __builtin_amdgcn_s_setprio(1); _Pragma("unroll") for (int m = 0; m < 4; ++m) _Pragma("unroll") for (int n = 0; n < 2; ++n) _Pragma("unroll") for (int k = 0; k < 2; ++k) \
;         acc[ai][bj][m][n] = __builtin_amdgcn_mfma_f32_16x16x32_bf16(Bt[n][k], At[m][k], acc[ai][bj][m][n], 0, 0, 0); __builtin_amdgcn_s_setprio(0); } while (0)
; #define PG8_WAIT_V(n) asm volatile("s_waitcnt vmcnt(" #n ")" ::: "memory")
; #define PG8_WAIT_L(n) asm volatile("s_waitcnt lgkmcnt(" #n ")" ::: "memory")
; #define PG8_BAR __builtin_amdgcn_s_barrier()
; #define PG8_SCHED __builtin_amdgcn_sched_barrier(0)
; template <class Epi, class Sched, bool ALIGN_EPI = false, bool SP2 = false>
; __device__ __forceinline__ void gemm_phase(PG8_LAS unsigned char* lds, const Gemm g, const Sched& S, const Epi& E) {
;     ...
;             PG8_LDB(B0, 0, 0); PG8_LDB(B1, 0, 1); PG8_SCHED; PG8_LDA(At, 0, 0); PG8_STAGE(PG8_SA(1, 1), a1 + hstep, voffA);
;             PG8_WAIT_V(8); PG8_WAIT_L(0); PG8_BAR; PG8_MMA(0, 0, At, B0); PG8_MMA(0, 1, At, B1); PG8_BAR; PG8_SCHED;
;             PG8_LDA(At, 0, 1); PG8_STAGE(PG8_SB(0, 0), b2, voffB); PG8_STAGE(PG8_SB(0, 1), b2 + hstep, voffB); PG8_STAGE(PG8_SA(0, 0), a2, voffA);
;             PG8_WAIT_V(8); PG8_WAIT_L(0); PG8_BAR; PG8_MMA(1, 0, At, B0); PG8_MMA(1, 1, At, B1); PG8_BAR; PG8_SCHED;
.LBB0_1647:
	s_add_u32 s6, s4, 0xfffc0080
	s_addc_u32 s7, s5, -1
	s_and_b64 s[0:1], s[0:1], exec
	s_cselect_b32 s7, s39, s7
	s_cselect_b32 s6, s47, s6
	s_cselect_b32 s1, s53, s56
	s_cselect_b32 s0, s54, s55
	s_cmp_eq_u32 s57, -2
	s_cselect_b32 vcc_lo, 1, 0
	s_cmp_gt_u32 s35, 1
	s_cselect_b32 vcc_lo, vcc_lo, 0
	s_add_i32 s58, 0, 0x10000
	v_add_u32_e32 v162, s58, v165
	s_add_i32 s60, 0, 0x14000
	ds_read_b128 v[132:135], v162
	ds_read_b128 v[136:139], v162 offset:1024
	ds_read_b128 v[140:143], v162 offset:2048
	ds_read_b128 v[180:183], v162 offset:3072
	v_add_u32_e32 v162, s60, v165
	ds_read_b128 v[200:203], v162
	ds_read_b128 v[204:207], v162 offset:1024
	ds_read_b128 v[208:211], v162 offset:2048
	ds_read_b128 v[212:215], v162 offset:3072
	v_lshl_add_u64 v[168:169], s[4:5], 0, v[158:159]
	s_add_i32 m0, s27, 0xc000
	ds_read_b128 v[216:219], v197
	ds_read_b128 v[220:223], v197 offset:1024
	ds_read_b128 v[224:227], v197 offset:2048
	ds_read_b128 v[228:231], v197 offset:3072
	ds_read_b128 v[232:235], v197 offset:4096
	ds_read_b128 v[236:239], v197 offset:5120
	ds_read_b128 v[240:243], v197 offset:6144
	ds_read_b128 v[244:247], v197 offset:7168
	global_load_lds_dwordx4 v[168:169], off
	v_lshl_add_u64 v[168:169], s[4:5], 0, v[160:161]
	s_add_i32 m0, s27, 0xe000
	s_nop 0
	global_load_lds_dwordx4 v[168:169], off
	s_waitcnt vmcnt(16)
	s_cmp_lg_u32 vcc_lo, 0
	s_cbranch_scc1 .Lgu_relaxed0
	s_waitcnt vmcnt(8)
.Lgu_relaxed0:
	s_waitcnt lgkmcnt(0)
	s_setprio 1
	s_barrier
	v_mfma_f32_16x16x32_bf16 v[124:127], v[132:135], v[216:219], v[124:127]
	v_mfma_f32_16x16x32_bf16 v[116:119], v[140:143], v[216:219], v[116:119]
	v_mfma_f32_16x16x32_bf16 v[108:111], v[132:135], v[224:227], v[108:111]
	v_mfma_f32_16x16x32_bf16 v[100:103], v[140:143], v[224:227], v[100:103]
	v_mfma_f32_16x16x32_bf16 v[92:95], v[132:135], v[232:235], v[92:95]
	v_mfma_f32_16x16x32_bf16 v[84:87], v[140:143], v[232:235], v[84:87]
	v_mfma_f32_16x16x32_bf16 v[76:79], v[132:135], v[240:243], v[76:79]
	v_mfma_f32_16x16x32_bf16 v[68:71], v[140:143], v[240:243], v[68:71]
	v_mfma_f32_16x16x32_bf16 v[124:127], v[136:139], v[220:223], v[124:127]
	v_mfma_f32_16x16x32_bf16 v[116:119], v[180:183], v[220:223], v[116:119]
	v_mfma_f32_16x16x32_bf16 v[108:111], v[136:139], v[228:231], v[108:111]
	v_mfma_f32_16x16x32_bf16 v[100:103], v[180:183], v[228:231], v[100:103]
	v_mfma_f32_16x16x32_bf16 v[92:95], v[136:139], v[236:239], v[92:95]
	v_mfma_f32_16x16x32_bf16 v[84:87], v[180:183], v[236:239], v[84:87]
	v_mfma_f32_16x16x32_bf16 v[76:79], v[136:139], v[244:247], v[76:79]
	v_mfma_f32_16x16x32_bf16 v[68:71], v[180:183], v[244:247], v[68:71]
	s_setprio 0
	s_setprio 1
	v_mfma_f32_16x16x32_bf16 v[120:123], v[200:203], v[216:219], v[120:123]
	v_mfma_f32_16x16x32_bf16 v[112:115], v[208:211], v[216:219], v[112:115]
	v_mfma_f32_16x16x32_bf16 v[104:107], v[200:203], v[224:227], v[104:107]
	v_mfma_f32_16x16x32_bf16 v[96:99], v[208:211], v[224:227], v[96:99]
	v_mfma_f32_16x16x32_bf16 v[88:91], v[200:203], v[232:235], v[88:91]
	v_mfma_f32_16x16x32_bf16 v[80:83], v[208:211], v[232:235], v[80:83]
	v_mfma_f32_16x16x32_bf16 v[72:75], v[200:203], v[240:243], v[72:75]
	v_mfma_f32_16x16x32_bf16 v[64:67], v[208:211], v[240:243], v[64:67]
	v_mfma_f32_16x16x32_bf16 v[120:123], v[204:207], v[220:223], v[120:123]
	v_mfma_f32_16x16x32_bf16 v[112:115], v[212:215], v[220:223], v[112:115]
	v_mfma_f32_16x16x32_bf16 v[104:107], v[204:207], v[228:231], v[104:107]
	v_mfma_f32_16x16x32_bf16 v[96:99], v[212:215], v[228:231], v[96:99]
	v_mfma_f32_16x16x32_bf16 v[88:91], v[204:207], v[236:239], v[88:91]
	v_mfma_f32_16x16x32_bf16 v[80:83], v[212:215], v[236:239], v[80:83]
	v_mfma_f32_16x16x32_bf16 v[72:75], v[204:207], v[244:247], v[72:75]
	v_mfma_f32_16x16x32_bf16 v[64:67], v[212:215], v[244:247], v[64:67]
	s_barrier
	s_setprio 0
	s_add_i32 s58, s58, s26
	v_lshl_add_u64 v[168:169], s[0:1], 0, v[144:145]
	s_mov_b32 m0, s58
	ds_read_b128 v[216:219], v197 offset:16384
	ds_read_b128 v[220:223], v197 offset:17408
	ds_read_b128 v[224:227], v197 offset:18432
	ds_read_b128 v[228:231], v197 offset:19456
	ds_read_b128 v[232:235], v197 offset:20480
	ds_read_b128 v[236:239], v197 offset:21504
	ds_read_b128 v[240:243], v197 offset:22528
	ds_read_b128 v[244:247], v197 offset:23552
	global_load_lds_dwordx4 v[168:169], off
	s_add_i32 m0, s58, 0x2000
	s_add_u32 s58, s0, 0x40000
	v_lshl_add_u64 v[172:173], s[0:1], 0, v[150:151]
	s_addc_u32 s59, s1, 0
	s_add_i32 s60, s60, s26
	global_load_lds_dwordx4 v[172:173], off
	v_lshl_add_u64 v[184:185], s[58:59], 0, v[144:145]
	s_mov_b32 m0, s60
	v_lshl_add_u64 v[186:187], s[6:7], 0, v[152:153]
	global_load_lds_dwordx4 v[184:185], off
	v_lshl_add_u64 v[184:185], s[58:59], 0, v[150:151]
	s_add_i32 m0, s60, 0x2000
	s_nop 0
	global_load_lds_dwordx4 v[184:185], off
	v_lshl_add_u64 v[184:185], s[6:7], 0, v[154:155]
	s_mov_b32 m0, s27
	s_nop 0
	global_load_lds_dwordx4 v[184:185], off
	s_mov_b32 m0, s28
	s_nop 0
	global_load_lds_dwordx4 v[186:187], off
	s_waitcnt vmcnt(16)
	s_cmp_lg_u32 vcc_lo, 0
	s_cbranch_scc1 .Lgu_relaxed1
	s_waitcnt vmcnt(8)
; #define PG8_STAGE(bufoff, gbase, voff) do { _Pragma("unroll") for (int _i = 0; _i < 2; ++_i) \
;         __builtin_amdgcn_global_load_lds((const unsigned*)((const char*)(gbase) + (voff)[_i]), (PG8_LAS unsigned*)(lds + (bufoff) + ldsw + _i * 8192), 16, 0, 0); } while (0)
; #define PG8_LDA(dst, b, h) do { _Pragma("unroll") for (int m = 0; m < 4; ++m) _Pragma("unroll") for (int k = 0; k < 2; ++k) dst[m][k] = *(const PG8_LAS bf16x8*)(lds + PG8_SA(b, h) + aoff + m * 2048 + k * 1024); } while (0)
; #define PG8_LDB(dst, b, h) do { _Pragma("unroll") for (int n = 0; n < 2; ++n) _Pragma("unroll") for (int k = 0; k < 2; ++k) dst[n][k] = *(const PG8_LAS bf16x8*)(lds + PG8_SB(b, h) + boff + n * 2048 + k * 1024); } while (0)
; #define PG8_MMA(ai, bj, At, Bt) do { __builtin_amdgcn_s_setprio(1); _Pragma("unroll") for (int m = 0; m < 4; ++m) _Pragma("unroll") for (int n = 0; n < 2; ++n) _Pragma("unroll") for (int k = 0; k < 2; ++k) \
;         acc[ai][bj][m][n] = __builtin_amdgcn_mfma_f32_16x16x32_bf16(Bt[n][k], At[m][k], acc[ai][bj][m][n], 0, 0, 0); __builtin_amdgcn_s_setprio(0); } while (0)
; #define PG8_WAIT_V(n) asm volatile("s_waitcnt vmcnt(" #n ")" ::: "memory")
; #define PG8_WAIT_L(n) asm volatile("s_waitcnt lgkmcnt(" #n ")" ::: "memory")
; #define PG8_BAR __builtin_amdgcn_s_barrier()
; #define PG8_SCHED __builtin_amdgcn_sched_barrier(0)
; template <class Epi, class Sched, bool ALIGN_EPI = false, bool SP2 = false>
; __device__ __forceinline__ void gemm_phase(PG8_LAS unsigned char* lds, const Gemm g, const Sched& S, const Epi& E) {
;     ...
;             PG8_WAIT_V(8); PG8_WAIT_L(0); PG8_BAR; PG8_MMA(0, 0, At, B0); PG8_MMA(0, 1, At, B1); PG8_BAR; PG8_SCHED;
;             PG8_LDA(At, 0, 1); PG8_STAGE(PG8_SB(0, 0), b2, voffB); PG8_STAGE(PG8_SB(0, 1), b2 + hstep, voffB); PG8_STAGE(PG8_SA(0, 0), a2, voffA);
;             PG8_WAIT_V(8); PG8_WAIT_L(0); PG8_BAR; PG8_MMA(1, 0, At, B0); PG8_MMA(1, 1, At, B1); PG8_BAR; PG8_SCHED;
;             PG8_LDB(B0, 1, 0); PG8_LDB(B1, 1, 1); PG8_SCHED; PG8_LDA(At, 1, 0); PG8_STAGE(PG8_SA(0, 1), a2 + hstep, voffA);
;             PG8_WAIT_V(8); PG8_WAIT_L(0); PG8_BAR; PG8_MMA(0, 0, At, B0); PG8_MMA(0, 1, At, B1); PG8_BAR; PG8_SCHED;
.Lgu_relaxed1:
	s_waitcnt lgkmcnt(0)
	s_setprio 1
	s_barrier
	v_mfma_f32_16x16x32_bf16 v[60:63], v[132:135], v[216:219], v[60:63]
	v_mfma_f32_16x16x32_bf16 v[52:55], v[140:143], v[216:219], v[52:55]
	v_mfma_f32_16x16x32_bf16 v[44:47], v[132:135], v[224:227], v[44:47]
	v_mfma_f32_16x16x32_bf16 v[36:39], v[140:143], v[224:227], v[36:39]
	v_mfma_f32_16x16x32_bf16 v[28:31], v[132:135], v[232:235], v[28:31]
	v_mfma_f32_16x16x32_bf16 v[20:23], v[140:143], v[232:235], v[20:23]
	v_mfma_f32_16x16x32_bf16 v[12:15], v[132:135], v[240:243], v[12:15]
	v_mfma_f32_16x16x32_bf16 v[4:7], v[140:143], v[240:243], v[4:7]
	v_mfma_f32_16x16x32_bf16 v[60:63], v[136:139], v[220:223], v[60:63]
	v_mfma_f32_16x16x32_bf16 v[52:55], v[180:183], v[220:223], v[52:55]
	v_mfma_f32_16x16x32_bf16 v[44:47], v[136:139], v[228:231], v[44:47]
	v_mfma_f32_16x16x32_bf16 v[36:39], v[180:183], v[228:231], v[36:39]
	v_mfma_f32_16x16x32_bf16 v[28:31], v[136:139], v[236:239], v[28:31]
	v_mfma_f32_16x16x32_bf16 v[20:23], v[180:183], v[236:239], v[20:23]
	v_mfma_f32_16x16x32_bf16 v[12:15], v[136:139], v[244:247], v[12:15]
	v_mfma_f32_16x16x32_bf16 v[4:7], v[180:183], v[244:247], v[4:7]
	s_setprio 0
	s_setprio 1
	v_mfma_f32_16x16x32_bf16 v[56:59], v[200:203], v[216:219], v[56:59]
	v_mfma_f32_16x16x32_bf16 v[48:51], v[208:211], v[216:219], v[48:51]
	v_mfma_f32_16x16x32_bf16 v[40:43], v[200:203], v[224:227], v[40:43]
	v_mfma_f32_16x16x32_bf16 v[32:35], v[208:211], v[224:227], v[32:35]
	v_mfma_f32_16x16x32_bf16 v[24:27], v[200:203], v[232:235], v[24:27]
	v_mfma_f32_16x16x32_bf16 v[16:19], v[208:211], v[232:235], v[16:19]
	v_mfma_f32_16x16x32_bf16 v[8:11], v[200:203], v[240:243], v[8:11]
	v_mfma_f32_16x16x32_bf16 v[0:3], v[208:211], v[240:243], v[0:3]
	v_mfma_f32_16x16x32_bf16 v[56:59], v[204:207], v[220:223], v[56:59]
	v_mfma_f32_16x16x32_bf16 v[48:51], v[212:215], v[220:223], v[48:51]
	v_mfma_f32_16x16x32_bf16 v[40:43], v[204:207], v[228:231], v[40:43]
	v_mfma_f32_16x16x32_bf16 v[32:35], v[212:215], v[228:231], v[32:35]
	v_mfma_f32_16x16x32_bf16 v[24:27], v[204:207], v[236:239], v[24:27]
	v_mfma_f32_16x16x32_bf16 v[16:19], v[212:215], v[236:239], v[16:19]
	v_mfma_f32_16x16x32_bf16 v[8:11], v[204:207], v[244:247], v[8:11]
	v_mfma_f32_16x16x32_bf16 v[0:3], v[212:215], v[244:247], v[0:3]
	s_barrier
	s_setprio 0
	s_add_i32 s58, 0, 0x18000
	v_add_u32_e32 v162, s58, v165
	s_add_i32 s59, 0, 0x1c000
	ds_read_b128 v[132:135], v162
	ds_read_b128 v[136:139], v162 offset:1024
	ds_read_b128 v[140:143], v162 offset:2048
	ds_read_b128 v[180:183], v162 offset:3072
	v_add_u32_e32 v162, s59, v165
	ds_read_b128 v[200:203], v162
	ds_read_b128 v[204:207], v162 offset:1024
	ds_read_b128 v[208:211], v162 offset:2048
	ds_read_b128 v[212:215], v162 offset:3072
	s_add_u32 s6, s6, 0x40000
	s_addc_u32 s7, s7, 0
	s_mov_b32 m0, s29
	v_lshl_add_u64 v[188:189], s[6:7], 0, v[154:155]
	ds_read_b128 v[216:219], v197 offset:32768
	ds_read_b128 v[220:223], v197 offset:33792
	ds_read_b128 v[224:227], v197 offset:34816
	ds_read_b128 v[228:231], v197 offset:35840
	ds_read_b128 v[232:235], v197 offset:36864
	ds_read_b128 v[236:239], v197 offset:37888
	ds_read_b128 v[240:243], v197 offset:38912
	ds_read_b128 v[244:247], v197 offset:39936
	global_load_lds_dwordx4 v[188:189], off
	v_lshl_add_u64 v[188:189], s[6:7], 0, v[152:153]
	s_mov_b32 m0, s30
	s_nop 0
	global_load_lds_dwordx4 v[188:189], off
	s_waitcnt vmcnt(8)
	s_waitcnt lgkmcnt(0)
	s_setprio 1
	s_barrier
	v_mfma_f32_16x16x32_bf16 v[124:127], v[132:135], v[216:219], v[124:127]
	v_mfma_f32_16x16x32_bf16 v[116:119], v[140:143], v[216:219], v[116:119]
	v_mfma_f32_16x16x32_bf16 v[108:111], v[132:135], v[224:227], v[108:111]
	v_mfma_f32_16x16x32_bf16 v[100:103], v[140:143], v[224:227], v[100:103]
	v_mfma_f32_16x16x32_bf16 v[92:95], v[132:135], v[232:235], v[92:95]
	v_mfma_f32_16x16x32_bf16 v[84:87], v[140:143], v[232:235], v[84:87]
	v_mfma_f32_16x16x32_bf16 v[76:79], v[132:135], v[240:243], v[76:79]
	v_mfma_f32_16x16x32_bf16 v[68:71], v[140:143], v[240:243], v[68:71]
	v_mfma_f32_16x16x32_bf16 v[124:127], v[136:139], v[220:223], v[124:127]
	v_mfma_f32_16x16x32_bf16 v[116:119], v[180:183], v[220:223], v[116:119]
	v_mfma_f32_16x16x32_bf16 v[108:111], v[136:139], v[228:231], v[108:111]
	v_mfma_f32_16x16x32_bf16 v[100:103], v[180:183], v[228:231], v[100:103]
	v_mfma_f32_16x16x32_bf16 v[92:95], v[136:139], v[236:239], v[92:95]
	v_mfma_f32_16x16x32_bf16 v[84:87], v[180:183], v[236:239], v[84:87]
	v_mfma_f32_16x16x32_bf16 v[76:79], v[136:139], v[244:247], v[76:79]
	v_mfma_f32_16x16x32_bf16 v[68:71], v[180:183], v[244:247], v[68:71]
	s_setprio 0
	s_setprio 1
	v_mfma_f32_16x16x32_bf16 v[120:123], v[200:203], v[216:219], v[120:123]
	v_mfma_f32_16x16x32_bf16 v[112:115], v[208:211], v[216:219], v[112:115]
	v_mfma_f32_16x16x32_bf16 v[104:107], v[200:203], v[224:227], v[104:107]
	v_mfma_f32_16x16x32_bf16 v[96:99], v[208:211], v[224:227], v[96:99]
	v_mfma_f32_16x16x32_bf16 v[88:91], v[200:203], v[232:235], v[88:91]
	v_mfma_f32_16x16x32_bf16 v[80:83], v[208:211], v[232:235], v[80:83]
	v_mfma_f32_16x16x32_bf16 v[72:75], v[200:203], v[240:243], v[72:75]
	v_mfma_f32_16x16x32_bf16 v[64:67], v[208:211], v[240:243], v[64:67]
	v_mfma_f32_16x16x32_bf16 v[120:123], v[204:207], v[220:223], v[120:123]
	v_mfma_f32_16x16x32_bf16 v[112:115], v[212:215], v[220:223], v[112:115]
	v_mfma_f32_16x16x32_bf16 v[104:107], v[204:207], v[228:231], v[104:107]
	v_mfma_f32_16x16x32_bf16 v[96:99], v[212:215], v[228:231], v[96:99]
	v_mfma_f32_16x16x32_bf16 v[88:91], v[204:207], v[236:239], v[88:91]
	v_mfma_f32_16x16x32_bf16 v[80:83], v[212:215], v[236:239], v[80:83]
	v_mfma_f32_16x16x32_bf16 v[72:75], v[204:207], v[244:247], v[72:75]
	v_mfma_f32_16x16x32_bf16 v[64:67], v[212:215], v[244:247], v[64:67]
	s_barrier
; #define PG8_STAGE(bufoff, gbase, voff) do { _Pragma("unroll") for (int _i = 0; _i < 2; ++_i) \
;         __builtin_amdgcn_global_load_lds((const unsigned*)((const char*)(gbase) + (voff)[_i]), (PG8_LAS unsigned*)(lds + (bufoff) + ldsw + _i * 8192), 16, 0, 0); } while (0)
; #define PG8_LDA(dst, b, h) do { _Pragma("unroll") for (int m = 0; m < 4; ++m) _Pragma("unroll") for (int k = 0; k < 2; ++k) dst[m][k] = *(const PG8_LAS bf16x8*)(lds + PG8_SA(b, h) + aoff + m * 2048 + k * 1024); } while (0)
; #define PG8_MMA(ai, bj, At, Bt) do { __builtin_amdgcn_s_setprio(1); _Pragma("unroll") for (int m = 0; m < 4; ++m) _Pragma("unroll") for (int n = 0; n < 2; ++n) _Pragma("unroll") for (int k = 0; k < 2; ++k) \
;         acc[ai][bj][m][n] = __builtin_amdgcn_mfma_f32_16x16x32_bf16(Bt[n][k], At[m][k], acc[ai][bj][m][n], 0, 0, 0); __builtin_amdgcn_s_setprio(0); } while (0)
; #define PG8_WAIT_V(n) asm volatile("s_waitcnt vmcnt(" #n ")" ::: "memory")
; #define PG8_WAIT_L(n) asm volatile("s_waitcnt lgkmcnt(" #n ")" ::: "memory")
; #define PG8_BAR __builtin_amdgcn_s_barrier()
; #define PG8_SCHED __builtin_amdgcn_sched_barrier(0)
; template <class Epi, class Sched, bool ALIGN_EPI = false, bool SP2 = false>
; __device__ __forceinline__ void gemm_phase(PG8_LAS unsigned char* lds, const Gemm g, const Sched& S, const Epi& E) {
;     ...
;             PG8_LDA(At, 1, 1); PG8_STAGE(PG8_SB(1, 0), b3, voffB); PG8_STAGE(PG8_SB(1, 1), b3 + hstep, voffB); PG8_STAGE(PG8_SA(1, 0), a3, voffA);
;             PG8_WAIT_V(8); PG8_WAIT_L(0); PG8_BAR; PG8_MMA(1, 0, At, B0); PG8_MMA(1, 1, At, B1); PG8_BAR; PG8_SCHED;
	s_setprio 0
	s_add_i32 s6, s58, s26
	v_lshl_add_u64 v[168:169], v[168:169], 0, s[94:95]
	s_mov_b32 m0, s6
	ds_read_b128 v[216:219], v197 offset:49152
	ds_read_b128 v[220:223], v197 offset:50176
	ds_read_b128 v[224:227], v197 offset:51200
	ds_read_b128 v[228:231], v197 offset:52224
	ds_read_b128 v[232:235], v197 offset:53248
	ds_read_b128 v[236:239], v197 offset:54272
	ds_read_b128 v[240:243], v197 offset:55296
	ds_read_b128 v[244:247], v197 offset:56320
	global_load_lds_dwordx4 v[168:169], off
	s_add_i32 m0, s6, 0x2000
	s_add_u32 s0, s0, 0x40080
	v_lshl_add_u64 v[168:169], v[172:173], 0, s[94:95]
	s_addc_u32 s1, s1, 0
	s_add_i32 s6, s59, s26
	global_load_lds_dwordx4 v[168:169], off
	v_lshl_add_u64 v[168:169], s[0:1], 0, v[144:145]
	s_mov_b32 m0, s6
	s_nop 0
	global_load_lds_dwordx4 v[168:169], off
	v_lshl_add_u64 v[168:169], s[0:1], 0, v[150:151]
	s_add_i32 m0, s6, 0x2000
	s_nop 0
	global_load_lds_dwordx4 v[168:169], off
	v_lshl_add_u64 v[168:169], v[184:185], 0, s[94:95]
	s_mov_b32 m0, s31
	s_nop 0
	global_load_lds_dwordx4 v[168:169], off
	v_lshl_add_u64 v[168:169], v[186:187], 0, s[94:95]
	s_mov_b32 m0, s34
	s_nop 0
	global_load_lds_dwordx4 v[168:169], off
	s_waitcnt vmcnt(8)
	s_waitcnt lgkmcnt(0)
	s_setprio 1
	s_barrier
	v_mfma_f32_16x16x32_bf16 v[60:63], v[132:135], v[216:219], v[60:63]
	v_mfma_f32_16x16x32_bf16 v[52:55], v[140:143], v[216:219], v[52:55]
	v_mfma_f32_16x16x32_bf16 v[44:47], v[132:135], v[224:227], v[44:47]
	v_mfma_f32_16x16x32_bf16 v[36:39], v[140:143], v[224:227], v[36:39]
	v_mfma_f32_16x16x32_bf16 v[28:31], v[132:135], v[232:235], v[28:31]
	v_mfma_f32_16x16x32_bf16 v[20:23], v[140:143], v[232:235], v[20:23]
	v_mfma_f32_16x16x32_bf16 v[12:15], v[132:135], v[240:243], v[12:15]
	v_mfma_f32_16x16x32_bf16 v[4:7], v[140:143], v[240:243], v[4:7]
	v_mfma_f32_16x16x32_bf16 v[60:63], v[136:139], v[220:223], v[60:63]
	v_mfma_f32_16x16x32_bf16 v[52:55], v[180:183], v[220:223], v[52:55]
	v_mfma_f32_16x16x32_bf16 v[44:47], v[136:139], v[228:231], v[44:47]
	v_mfma_f32_16x16x32_bf16 v[36:39], v[180:183], v[228:231], v[36:39]
	v_mfma_f32_16x16x32_bf16 v[28:31], v[136:139], v[236:239], v[28:31]
	v_mfma_f32_16x16x32_bf16 v[20:23], v[180:183], v[236:239], v[20:23]
	v_mfma_f32_16x16x32_bf16 v[12:15], v[136:139], v[244:247], v[12:15]
	v_mfma_f32_16x16x32_bf16 v[4:7], v[180:183], v[244:247], v[4:7]
	s_setprio 0
	s_setprio 1
	v_mfma_f32_16x16x32_bf16 v[56:59], v[200:203], v[216:219], v[56:59]
	v_mfma_f32_16x16x32_bf16 v[48:51], v[208:211], v[216:219], v[48:51]
	v_mfma_f32_16x16x32_bf16 v[40:43], v[200:203], v[224:227], v[40:43]
	v_mfma_f32_16x16x32_bf16 v[32:35], v[208:211], v[224:227], v[32:35]
	v_mfma_f32_16x16x32_bf16 v[24:27], v[200:203], v[232:235], v[24:27]
	v_mfma_f32_16x16x32_bf16 v[16:19], v[208:211], v[232:235], v[16:19]
	v_mfma_f32_16x16x32_bf16 v[8:11], v[200:203], v[240:243], v[8:11]
	v_mfma_f32_16x16x32_bf16 v[0:3], v[208:211], v[240:243], v[0:3]
	v_mfma_f32_16x16x32_bf16 v[56:59], v[204:207], v[220:223], v[56:59]
	v_mfma_f32_16x16x32_bf16 v[48:51], v[212:215], v[220:223], v[48:51]
	v_mfma_f32_16x16x32_bf16 v[40:43], v[204:207], v[228:231], v[40:43]
	v_mfma_f32_16x16x32_bf16 v[32:35], v[212:215], v[228:231], v[32:35]
	v_mfma_f32_16x16x32_bf16 v[24:27], v[204:207], v[236:239], v[24:27]
	v_mfma_f32_16x16x32_bf16 v[16:19], v[212:215], v[236:239], v[16:19]
	v_mfma_f32_16x16x32_bf16 v[8:11], v[204:207], v[244:247], v[8:11]
	v_mfma_f32_16x16x32_bf16 v[0:3], v[212:215], v[244:247], v[0:3]
	s_barrier
	s_setprio 0
	s_add_i32 s57, s57, 2
	s_add_u32 s4, s4, 0x100
	s_addc_u32 s5, s5, 0
	s_add_u32 s55, s55, 0x100
	s_addc_u32 s56, s56, 0
	s_cmp_gt_u32 s57, 13
	s_cbranch_scc1 .LBB0_1650
